# hand-written composed-pool-weights item with exact-f32 MFMA 16x16x4 (20.8us -> 7us per item), on top of v40
# speedup vs baseline: 1.0057x; 1.0057x over previous
.LBB0_98:
	s_andn2_b64 vcc, exec, s[52:53]
	s_cbranch_vccnz .LBB0_102
	s_load_dwordx2 s[6:7], s[0:1], 0x98
	s_load_dwordx2 s[8:9], s[0:1], 0xa0
	s_load_dwordx2 s[52:53], s[0:1], 0xb0
	s_load_dwordx2 s[54:55], s[0:1], 0xe0
	s_add_i32 s36, s44, 0xffffff80
	s_lshr_b32 s45, s36, 4
	s_and_b32 s36, s36, 15
	s_lshl_b32 s36, s36, 6
	v_lshlrev_b32_e32 v2, 4, v79
	v_lshrrev_b32_e32 v3, 5, v79
	v_mul_u32_u24_e32 v3, 528, v3
	v_and_b32_e32 v4, 31, v79
	v_lshl_add_u32 v3, v4, 4, v3
	v_lshrrev_b32_e32 v4, 4, v79
	v_lshlrev_b32_e32 v5, 2, v4
	v_lshlrev_b32_e32 v4, 12, v4
	v_and_b32_e32 v6, 15, v79
	v_lshl_add_u32 v4, v6, 4, v4
	v_add_u32_e32 v6, 0x10800, v2
	s_waitcnt lgkmcnt(0)
	s_lshl_b32 s56, s45, 16
	s_add_u32 s6, s6, s56
	s_addc_u32 s7, s7, 0
	s_lshl_b32 s56, s45, 9
	s_add_u32 s8, s8, s56
	s_addc_u32 s9, s9, 0
	s_lshl_b32 s56, s45, 19
	s_lshl_b32 s57, s36, 2
	s_add_i32 s56, s56, s57
	s_add_u32 s52, s52, s56
	s_addc_u32 s53, s53, 0
	global_load_dwordx4 v[106:109], v2, s[6:7]
	s_add_u32 s6, s6, 0x2000
	s_addc_u32 s7, s7, 0
	global_load_dwordx4 v[110:113], v2, s[6:7]
	s_add_u32 s6, s6, 0x2000
	s_addc_u32 s7, s7, 0
	global_load_dwordx4 v[114:117], v2, s[6:7]
	s_add_u32 s6, s6, 0x2000
	s_addc_u32 s7, s7, 0
	global_load_dwordx4 v[118:121], v2, s[6:7]
	s_add_u32 s6, s6, 0x2000
	s_addc_u32 s7, s7, 0
	global_load_dwordx4 v[122:125], v2, s[6:7]
	s_add_u32 s6, s6, 0x2000
	s_addc_u32 s7, s7, 0
	global_load_dwordx4 v[126:129], v2, s[6:7]
	s_add_u32 s6, s6, 0x2000
	s_addc_u32 s7, s7, 0
	global_load_dwordx4 v[130:133], v2, s[6:7]
	s_add_u32 s6, s6, 0x2000
	s_addc_u32 s7, s7, 0
	global_load_dwordx4 v[134:137], v2, s[6:7]
	global_load_dwordx4 v[138:141], v4, s[52:53]
	s_add_u32 s52, s52, 0x20000
	s_addc_u32 s53, s53, 0
	global_load_dwordx4 v[142:145], v4, s[52:53]
	s_add_u32 s52, s52, 0x20000
	s_addc_u32 s53, s53, 0
	global_load_dwordx4 v[146:149], v4, s[52:53]
	s_add_u32 s52, s52, 0x20000
	s_addc_u32 s53, s53, 0
	global_load_dwordx4 v[150:153], v4, s[52:53]
	global_load_dword v50, v5, s[8:9]
	global_load_dword v52, v5, s[8:9] offset:128
	global_load_dword v54, v5, s[8:9] offset:256
	global_load_dword v56, v5, s[8:9] offset:384
	v_and_b32_e32 v7, 15, v80
	v_lshrrev_b32_e32 v8, 4, v80
	v_mul_u32_u24_e32 v9, 528, v7
	v_lshl_add_u32 v9, v8, 7, v9
	s_mul_i32 s56, s29, 8448
	v_add_u32_e32 v9, s56, v9
	v_lshlrev_b32_e32 v58, 13, v8
	v_lshl_add_u32 v58, v7, 2, v58
	v_add_u32_e32 v58, 0x10800, v58
	v_mov_b32_e32 v154, 0
	v_mov_b32_e32 v155, 0
	v_mov_b32_e32 v156, 0
	v_mov_b32_e32 v157, 0
	v_mov_b32_e32 v158, 0
	v_mov_b32_e32 v159, 0
	v_mov_b32_e32 v160, 0
	v_mov_b32_e32 v161, 0
	v_mov_b32_e32 v162, 0
	v_mov_b32_e32 v163, 0
	v_mov_b32_e32 v164, 0
	v_mov_b32_e32 v165, 0
	v_mov_b32_e32 v166, 0
	v_mov_b32_e32 v167, 0
	v_mov_b32_e32 v168, 0
	v_mov_b32_e32 v169, 0
	s_waitcnt vmcnt(0)
	ds_write_b128 v3, v[106:109]
	ds_write_b128 v3, v[110:113] offset:8448
	ds_write_b128 v3, v[114:117] offset:16896
	ds_write_b128 v3, v[118:121] offset:25344
	ds_write_b128 v3, v[122:125] offset:33792
	ds_write_b128 v3, v[126:129] offset:42240
	ds_write_b128 v3, v[130:133] offset:50688
	ds_write_b128 v3, v[134:137] offset:59136
	v_pk_mul_f32 v[138:139], v[138:139], v[50:51] op_sel_hi:[1,0]
	v_pk_mul_f32 v[140:141], v[140:141], v[50:51] op_sel_hi:[1,0]
	v_pk_mul_f32 v[142:143], v[142:143], v[52:53] op_sel_hi:[1,0]
	v_pk_mul_f32 v[144:145], v[144:145], v[52:53] op_sel_hi:[1,0]
	v_pk_mul_f32 v[146:147], v[146:147], v[54:55] op_sel_hi:[1,0]
	v_pk_mul_f32 v[148:149], v[148:149], v[54:55] op_sel_hi:[1,0]
	v_pk_mul_f32 v[150:151], v[150:151], v[56:57] op_sel_hi:[1,0]
	v_pk_mul_f32 v[152:153], v[152:153], v[56:57] op_sel_hi:[1,0]
	ds_write_b128 v6, v[138:141]
	ds_write_b128 v6, v[142:145] offset:8192
	ds_write_b128 v6, v[146:149] offset:16384
	ds_write_b128 v6, v[150:153] offset:24576
	s_waitcnt lgkmcnt(0)
	s_barrier
	ds_read_b128 v[10:13], v9
	ds_read_b32 v14, v58
	ds_read_b32 v15, v58 offset:64
	ds_read_b32 v16, v58 offset:128
	ds_read_b32 v17, v58 offset:192
	ds_read_b32 v18, v58 offset:256
	ds_read_b32 v19, v58 offset:320
	ds_read_b32 v20, v58 offset:384
	ds_read_b32 v21, v58 offset:448
	ds_read_b32 v22, v58 offset:512
	ds_read_b32 v23, v58 offset:576
	ds_read_b32 v24, v58 offset:640
	ds_read_b32 v25, v58 offset:704
	ds_read_b32 v26, v58 offset:768
	ds_read_b32 v27, v58 offset:832
	ds_read_b32 v28, v58 offset:896
	ds_read_b32 v29, v58 offset:960
	s_waitcnt lgkmcnt(0)
	ds_read_b128 v[30:33], v9 offset:16
	ds_read_b32 v34, v58 offset:1024
	ds_read_b32 v35, v58 offset:1088
	ds_read_b32 v36, v58 offset:1152
	ds_read_b32 v37, v58 offset:1216
	ds_read_b32 v38, v58 offset:1280
	ds_read_b32 v39, v58 offset:1344
	ds_read_b32 v40, v58 offset:1408
	v_mfma_f32_16x16x4_f32 v[154:157], v10, v14, v[154:157]
	v_mfma_f32_16x16x4_f32 v[158:161], v10, v15, v[158:161]
	v_mfma_f32_16x16x4_f32 v[162:165], v10, v16, v[162:165]
	v_mfma_f32_16x16x4_f32 v[166:169], v10, v17, v[166:169]
	v_mfma_f32_16x16x4_f32 v[154:157], v11, v18, v[154:157]
	v_mfma_f32_16x16x4_f32 v[158:161], v11, v19, v[158:161]
	v_mfma_f32_16x16x4_f32 v[162:165], v11, v20, v[162:165]
	v_mfma_f32_16x16x4_f32 v[166:169], v11, v21, v[166:169]
	ds_read_b32 v41, v58 offset:1472
	ds_read_b32 v42, v58 offset:1536
	ds_read_b32 v43, v58 offset:1600
	ds_read_b32 v44, v58 offset:1664
	ds_read_b32 v45, v58 offset:1728
	ds_read_b32 v46, v58 offset:1792
	ds_read_b32 v47, v58 offset:1856
	ds_read_b32 v48, v58 offset:1920
	ds_read_b32 v49, v58 offset:1984
	v_mfma_f32_16x16x4_f32 v[154:157], v12, v22, v[154:157]
	v_mfma_f32_16x16x4_f32 v[158:161], v12, v23, v[158:161]
	v_mfma_f32_16x16x4_f32 v[162:165], v12, v24, v[162:165]
	v_mfma_f32_16x16x4_f32 v[166:169], v12, v25, v[166:169]
	v_mfma_f32_16x16x4_f32 v[154:157], v13, v26, v[154:157]
	v_mfma_f32_16x16x4_f32 v[158:161], v13, v27, v[158:161]
	v_mfma_f32_16x16x4_f32 v[162:165], v13, v28, v[162:165]
	v_mfma_f32_16x16x4_f32 v[166:169], v13, v29, v[166:169]
	s_waitcnt lgkmcnt(0)
	ds_read_b128 v[10:13], v9 offset:32
	ds_read_b32 v14, v58 offset:2048
	ds_read_b32 v15, v58 offset:2112
	ds_read_b32 v16, v58 offset:2176
	ds_read_b32 v17, v58 offset:2240
	ds_read_b32 v18, v58 offset:2304
	ds_read_b32 v19, v58 offset:2368
	ds_read_b32 v20, v58 offset:2432
	v_mfma_f32_16x16x4_f32 v[154:157], v30, v34, v[154:157]
	v_mfma_f32_16x16x4_f32 v[158:161], v30, v35, v[158:161]
	v_mfma_f32_16x16x4_f32 v[162:165], v30, v36, v[162:165]
	v_mfma_f32_16x16x4_f32 v[166:169], v30, v37, v[166:169]
	v_mfma_f32_16x16x4_f32 v[154:157], v31, v38, v[154:157]
	v_mfma_f32_16x16x4_f32 v[158:161], v31, v39, v[158:161]
	v_mfma_f32_16x16x4_f32 v[162:165], v31, v40, v[162:165]
	v_mfma_f32_16x16x4_f32 v[166:169], v31, v41, v[166:169]
	ds_read_b32 v21, v58 offset:2496
	ds_read_b32 v22, v58 offset:2560
	ds_read_b32 v23, v58 offset:2624
	ds_read_b32 v24, v58 offset:2688
	ds_read_b32 v25, v58 offset:2752
	ds_read_b32 v26, v58 offset:2816
	ds_read_b32 v27, v58 offset:2880
	ds_read_b32 v28, v58 offset:2944
	ds_read_b32 v29, v58 offset:3008
	v_mfma_f32_16x16x4_f32 v[154:157], v32, v42, v[154:157]
	v_mfma_f32_16x16x4_f32 v[158:161], v32, v43, v[158:161]
	v_mfma_f32_16x16x4_f32 v[162:165], v32, v44, v[162:165]
	v_mfma_f32_16x16x4_f32 v[166:169], v32, v45, v[166:169]
	v_mfma_f32_16x16x4_f32 v[154:157], v33, v46, v[154:157]
	v_mfma_f32_16x16x4_f32 v[158:161], v33, v47, v[158:161]
	v_mfma_f32_16x16x4_f32 v[162:165], v33, v48, v[162:165]
	v_mfma_f32_16x16x4_f32 v[166:169], v33, v49, v[166:169]
	s_waitcnt lgkmcnt(0)
	ds_read_b128 v[30:33], v9 offset:48
	ds_read_b32 v34, v58 offset:3072
	ds_read_b32 v35, v58 offset:3136
	ds_read_b32 v36, v58 offset:3200
	ds_read_b32 v37, v58 offset:3264
	ds_read_b32 v38, v58 offset:3328
	ds_read_b32 v39, v58 offset:3392
	ds_read_b32 v40, v58 offset:3456
	v_mfma_f32_16x16x4_f32 v[154:157], v10, v14, v[154:157]
	v_mfma_f32_16x16x4_f32 v[158:161], v10, v15, v[158:161]
	v_mfma_f32_16x16x4_f32 v[162:165], v10, v16, v[162:165]
	v_mfma_f32_16x16x4_f32 v[166:169], v10, v17, v[166:169]
	v_mfma_f32_16x16x4_f32 v[154:157], v11, v18, v[154:157]
	v_mfma_f32_16x16x4_f32 v[158:161], v11, v19, v[158:161]
	v_mfma_f32_16x16x4_f32 v[162:165], v11, v20, v[162:165]
	v_mfma_f32_16x16x4_f32 v[166:169], v11, v21, v[166:169]
	ds_read_b32 v41, v58 offset:3520
	ds_read_b32 v42, v58 offset:3584
	ds_read_b32 v43, v58 offset:3648
	ds_read_b32 v44, v58 offset:3712
	ds_read_b32 v45, v58 offset:3776
	ds_read_b32 v46, v58 offset:3840
	ds_read_b32 v47, v58 offset:3904
	ds_read_b32 v48, v58 offset:3968
	ds_read_b32 v49, v58 offset:4032
	v_mfma_f32_16x16x4_f32 v[154:157], v12, v22, v[154:157]
	v_mfma_f32_16x16x4_f32 v[158:161], v12, v23, v[158:161]
	v_mfma_f32_16x16x4_f32 v[162:165], v12, v24, v[162:165]
	v_mfma_f32_16x16x4_f32 v[166:169], v12, v25, v[166:169]
	v_mfma_f32_16x16x4_f32 v[154:157], v13, v26, v[154:157]
	v_mfma_f32_16x16x4_f32 v[158:161], v13, v27, v[158:161]
	v_mfma_f32_16x16x4_f32 v[162:165], v13, v28, v[162:165]
	v_mfma_f32_16x16x4_f32 v[166:169], v13, v29, v[166:169]
	s_waitcnt lgkmcnt(0)
	ds_read_b128 v[10:13], v9 offset:64
	ds_read_b32 v14, v58 offset:4096
	ds_read_b32 v15, v58 offset:4160
	ds_read_b32 v16, v58 offset:4224
	ds_read_b32 v17, v58 offset:4288
	ds_read_b32 v18, v58 offset:4352
	ds_read_b32 v19, v58 offset:4416
	ds_read_b32 v20, v58 offset:4480
	v_mfma_f32_16x16x4_f32 v[154:157], v30, v34, v[154:157]
	v_mfma_f32_16x16x4_f32 v[158:161], v30, v35, v[158:161]
	v_mfma_f32_16x16x4_f32 v[162:165], v30, v36, v[162:165]
	v_mfma_f32_16x16x4_f32 v[166:169], v30, v37, v[166:169]
	v_mfma_f32_16x16x4_f32 v[154:157], v31, v38, v[154:157]
	v_mfma_f32_16x16x4_f32 v[158:161], v31, v39, v[158:161]
	v_mfma_f32_16x16x4_f32 v[162:165], v31, v40, v[162:165]
	v_mfma_f32_16x16x4_f32 v[166:169], v31, v41, v[166:169]
	ds_read_b32 v21, v58 offset:4544
	ds_read_b32 v22, v58 offset:4608
	ds_read_b32 v23, v58 offset:4672
	ds_read_b32 v24, v58 offset:4736
	ds_read_b32 v25, v58 offset:4800
	ds_read_b32 v26, v58 offset:4864
	ds_read_b32 v27, v58 offset:4928
	ds_read_b32 v28, v58 offset:4992
	ds_read_b32 v29, v58 offset:5056
	v_mfma_f32_16x16x4_f32 v[154:157], v32, v42, v[154:157]
	v_mfma_f32_16x16x4_f32 v[158:161], v32, v43, v[158:161]
	v_mfma_f32_16x16x4_f32 v[162:165], v32, v44, v[162:165]
	v_mfma_f32_16x16x4_f32 v[166:169], v32, v45, v[166:169]
	v_mfma_f32_16x16x4_f32 v[154:157], v33, v46, v[154:157]
	v_mfma_f32_16x16x4_f32 v[158:161], v33, v47, v[158:161]
	v_mfma_f32_16x16x4_f32 v[162:165], v33, v48, v[162:165]
	v_mfma_f32_16x16x4_f32 v[166:169], v33, v49, v[166:169]
	s_waitcnt lgkmcnt(0)
	ds_read_b128 v[30:33], v9 offset:80
	ds_read_b32 v34, v58 offset:5120
	ds_read_b32 v35, v58 offset:5184
	ds_read_b32 v36, v58 offset:5248
	ds_read_b32 v37, v58 offset:5312
	ds_read_b32 v38, v58 offset:5376
	ds_read_b32 v39, v58 offset:5440
	ds_read_b32 v40, v58 offset:5504
	v_mfma_f32_16x16x4_f32 v[154:157], v10, v14, v[154:157]
	v_mfma_f32_16x16x4_f32 v[158:161], v10, v15, v[158:161]
	v_mfma_f32_16x16x4_f32 v[162:165], v10, v16, v[162:165]
	v_mfma_f32_16x16x4_f32 v[166:169], v10, v17, v[166:169]
	v_mfma_f32_16x16x4_f32 v[154:157], v11, v18, v[154:157]
	v_mfma_f32_16x16x4_f32 v[158:161], v11, v19, v[158:161]
	v_mfma_f32_16x16x4_f32 v[162:165], v11, v20, v[162:165]
	v_mfma_f32_16x16x4_f32 v[166:169], v11, v21, v[166:169]
	ds_read_b32 v41, v58 offset:5568
	ds_read_b32 v42, v58 offset:5632
	ds_read_b32 v43, v58 offset:5696
	ds_read_b32 v44, v58 offset:5760
	ds_read_b32 v45, v58 offset:5824
	ds_read_b32 v46, v58 offset:5888
	ds_read_b32 v47, v58 offset:5952
	ds_read_b32 v48, v58 offset:6016
	ds_read_b32 v49, v58 offset:6080
	v_mfma_f32_16x16x4_f32 v[154:157], v12, v22, v[154:157]
	v_mfma_f32_16x16x4_f32 v[158:161], v12, v23, v[158:161]
	v_mfma_f32_16x16x4_f32 v[162:165], v12, v24, v[162:165]
	v_mfma_f32_16x16x4_f32 v[166:169], v12, v25, v[166:169]
	v_mfma_f32_16x16x4_f32 v[154:157], v13, v26, v[154:157]
	v_mfma_f32_16x16x4_f32 v[158:161], v13, v27, v[158:161]
	v_mfma_f32_16x16x4_f32 v[162:165], v13, v28, v[162:165]
	v_mfma_f32_16x16x4_f32 v[166:169], v13, v29, v[166:169]
	s_waitcnt lgkmcnt(0)
	ds_read_b128 v[10:13], v9 offset:96
	ds_read_b32 v14, v58 offset:6144
	ds_read_b32 v15, v58 offset:6208
	ds_read_b32 v16, v58 offset:6272
	ds_read_b32 v17, v58 offset:6336
	ds_read_b32 v18, v58 offset:6400
	ds_read_b32 v19, v58 offset:6464
	ds_read_b32 v20, v58 offset:6528
	v_mfma_f32_16x16x4_f32 v[154:157], v30, v34, v[154:157]
	v_mfma_f32_16x16x4_f32 v[158:161], v30, v35, v[158:161]
	v_mfma_f32_16x16x4_f32 v[162:165], v30, v36, v[162:165]
	v_mfma_f32_16x16x4_f32 v[166:169], v30, v37, v[166:169]
	v_mfma_f32_16x16x4_f32 v[154:157], v31, v38, v[154:157]
	v_mfma_f32_16x16x4_f32 v[158:161], v31, v39, v[158:161]
	v_mfma_f32_16x16x4_f32 v[162:165], v31, v40, v[162:165]
	v_mfma_f32_16x16x4_f32 v[166:169], v31, v41, v[166:169]
	ds_read_b32 v21, v58 offset:6592
	ds_read_b32 v22, v58 offset:6656
	ds_read_b32 v23, v58 offset:6720
	ds_read_b32 v24, v58 offset:6784
	ds_read_b32 v25, v58 offset:6848
	ds_read_b32 v26, v58 offset:6912
	ds_read_b32 v27, v58 offset:6976
	ds_read_b32 v28, v58 offset:7040
	ds_read_b32 v29, v58 offset:7104
	v_mfma_f32_16x16x4_f32 v[154:157], v32, v42, v[154:157]
	v_mfma_f32_16x16x4_f32 v[158:161], v32, v43, v[158:161]
	v_mfma_f32_16x16x4_f32 v[162:165], v32, v44, v[162:165]
	v_mfma_f32_16x16x4_f32 v[166:169], v32, v45, v[166:169]
	v_mfma_f32_16x16x4_f32 v[154:157], v33, v46, v[154:157]
	v_mfma_f32_16x16x4_f32 v[158:161], v33, v47, v[158:161]
	v_mfma_f32_16x16x4_f32 v[162:165], v33, v48, v[162:165]
	v_mfma_f32_16x16x4_f32 v[166:169], v33, v49, v[166:169]
	s_waitcnt lgkmcnt(0)
	ds_read_b128 v[30:33], v9 offset:112
	ds_read_b32 v34, v58 offset:7168
	ds_read_b32 v35, v58 offset:7232
	ds_read_b32 v36, v58 offset:7296
	ds_read_b32 v37, v58 offset:7360
	ds_read_b32 v38, v58 offset:7424
	ds_read_b32 v39, v58 offset:7488
	ds_read_b32 v40, v58 offset:7552
	v_mfma_f32_16x16x4_f32 v[154:157], v10, v14, v[154:157]
	v_mfma_f32_16x16x4_f32 v[158:161], v10, v15, v[158:161]
	v_mfma_f32_16x16x4_f32 v[162:165], v10, v16, v[162:165]
	v_mfma_f32_16x16x4_f32 v[166:169], v10, v17, v[166:169]
	v_mfma_f32_16x16x4_f32 v[154:157], v11, v18, v[154:157]
	v_mfma_f32_16x16x4_f32 v[158:161], v11, v19, v[158:161]
	v_mfma_f32_16x16x4_f32 v[162:165], v11, v20, v[162:165]
	v_mfma_f32_16x16x4_f32 v[166:169], v11, v21, v[166:169]
	ds_read_b32 v41, v58 offset:7616
	ds_read_b32 v42, v58 offset:7680
	ds_read_b32 v43, v58 offset:7744
	ds_read_b32 v44, v58 offset:7808
	ds_read_b32 v45, v58 offset:7872
	ds_read_b32 v46, v58 offset:7936
	ds_read_b32 v47, v58 offset:8000
	ds_read_b32 v48, v58 offset:8064
	ds_read_b32 v49, v58 offset:8128
	v_mfma_f32_16x16x4_f32 v[154:157], v12, v22, v[154:157]
	v_mfma_f32_16x16x4_f32 v[158:161], v12, v23, v[158:161]
	v_mfma_f32_16x16x4_f32 v[162:165], v12, v24, v[162:165]
	v_mfma_f32_16x16x4_f32 v[166:169], v12, v25, v[166:169]
	v_mfma_f32_16x16x4_f32 v[154:157], v13, v26, v[154:157]
	v_mfma_f32_16x16x4_f32 v[158:161], v13, v27, v[158:161]
	v_mfma_f32_16x16x4_f32 v[162:165], v13, v28, v[162:165]
	v_mfma_f32_16x16x4_f32 v[166:169], v13, v29, v[166:169]
	s_waitcnt lgkmcnt(0)
	v_mfma_f32_16x16x4_f32 v[154:157], v30, v34, v[154:157]
	v_mfma_f32_16x16x4_f32 v[158:161], v30, v35, v[158:161]
	v_mfma_f32_16x16x4_f32 v[162:165], v30, v36, v[162:165]
	v_mfma_f32_16x16x4_f32 v[166:169], v30, v37, v[166:169]
	v_mfma_f32_16x16x4_f32 v[154:157], v31, v38, v[154:157]
	v_mfma_f32_16x16x4_f32 v[158:161], v31, v39, v[158:161]
	v_mfma_f32_16x16x4_f32 v[162:165], v31, v40, v[162:165]
	v_mfma_f32_16x16x4_f32 v[166:169], v31, v41, v[166:169]
	v_mfma_f32_16x16x4_f32 v[154:157], v32, v42, v[154:157]
	v_mfma_f32_16x16x4_f32 v[158:161], v32, v43, v[158:161]
	v_mfma_f32_16x16x4_f32 v[162:165], v32, v44, v[162:165]
	v_mfma_f32_16x16x4_f32 v[166:169], v32, v45, v[166:169]
	v_mfma_f32_16x16x4_f32 v[154:157], v33, v46, v[154:157]
	v_mfma_f32_16x16x4_f32 v[158:161], v33, v47, v[158:161]
	v_mfma_f32_16x16x4_f32 v[162:165], v33, v48, v[162:165]
	v_mfma_f32_16x16x4_f32 v[166:169], v33, v49, v[166:169]
	s_lshl_b32 s56, s36, 11
	s_lshl_b32 s57, s45, 8
	s_add_i32 s56, s56, s57
	s_lshl_b32 s57, s29, 5
	s_add_i32 s56, s56, s57
	s_add_i32 s56, s56, 0x900400
	s_add_u32 s54, s54, s56
	s_addc_u32 s55, s55, 0
	v_lshlrev_b32_e32 v2, 11, v7
	v_lshl_add_u32 v2, v8, 3, v2
	s_mov_b64 s[6:7], s[48:49]
	s_nop 15
	v_cvt_pk_bf16_f32 v10, v154, v155
	v_cvt_pk_bf16_f32 v11, v156, v157
	v_cvt_pk_bf16_f32 v12, v158, v159
	v_cvt_pk_bf16_f32 v13, v160, v161
	v_cvt_pk_bf16_f32 v14, v162, v163
	v_cvt_pk_bf16_f32 v15, v164, v165
	v_cvt_pk_bf16_f32 v16, v166, v167
	v_cvt_pk_bf16_f32 v17, v168, v169
	global_store_dwordx2 v2, v[10:11], s[54:55]
	v_add_u32_e32 v3, 0x8000, v2
	global_store_dwordx2 v3, v[12:13], s[54:55]
	v_add_u32_e32 v3, 0x10000, v2
	global_store_dwordx2 v3, v[14:15], s[54:55]
	v_add_u32_e32 v3, 0x18000, v2
	global_store_dwordx2 v3, v[16:17], s[54:55]
	s_barrier
